# P7 pass-1 scan loop: premature vmcnt waits and their consumers moved below the 24-load burst (on top of the P5 rewrite)
# baseline (speedup 1.0000x reference)
.LBB0_1042:
	v_add_co_u32_e32 v14, vcc, 0x4000, v2
	global_load_dword v16, v[2:3], off
	s_nop 0
	v_addc_co_u32_e32 v15, vcc, 0, v3, vcc
	v_add_co_u32_e32 v18, vcc, 0x8000, v2
	s_add_i32 s20, s20, 24
	s_nop 0
	v_addc_co_u32_e32 v19, vcc, 0, v3, vcc
	v_add_co_u32_e32 v20, vcc, 0xc000, v2
	global_load_dword v17, v[14:15], off
	global_load_dword v22, v[18:19], off
	v_addc_co_u32_e32 v21, vcc, 0, v3, vcc
	v_add_co_u32_e32 v14, vcc, 0x10000, v2
	s_mov_b64 s[26:27], 0x60000
	s_nop 0
	v_addc_co_u32_e32 v15, vcc, 0, v3, vcc
	v_add_co_u32_e32 v18, vcc, 0x14000, v2
	global_load_dword v23, v[20:21], off
	global_load_dword v24, v[14:15], off
	v_addc_co_u32_e32 v19, vcc, 0, v3, vcc
	v_add_co_u32_e32 v14, vcc, 0x18000, v2
	s_cmpk_gt_u32 s20, 0xd7
	s_nop 0
	v_addc_co_u32_e32 v15, vcc, 0, v3, vcc
	v_add_co_u32_e32 v20, vcc, 0x1c000, v2
	global_load_dword v25, v[18:19], off
	global_load_dword v27, v[14:15], off
	v_addc_co_u32_e32 v21, vcc, 0, v3, vcc
	v_add_co_u32_e32 v14, vcc, 0x20000, v2
	s_nop 0
	s_nop 0
	v_addc_co_u32_e32 v15, vcc, 0, v3, vcc
	v_add_co_u32_e32 v18, vcc, 0x24000, v2
	global_load_dword v28, v[20:21], off
	global_load_dword v30, v[14:15], off
	v_addc_co_u32_e32 v19, vcc, 0, v3, vcc
	v_add_co_u32_e32 v14, vcc, 0x28000, v2
	s_nop 0
	s_nop 0
	v_addc_co_u32_e32 v15, vcc, 0, v3, vcc
	v_add_co_u32_e32 v20, vcc, 0x2c000, v2
	global_load_dword v32, v[18:19], off
	global_load_dword v34, v[14:15], off
	v_addc_co_u32_e32 v21, vcc, 0, v3, vcc
	v_add_co_u32_e32 v14, vcc, 0x30000, v2
	s_nop 0
	s_nop 0
	v_addc_co_u32_e32 v15, vcc, 0, v3, vcc
	v_add_co_u32_e32 v18, vcc, 0x34000, v2
	global_load_dword v36, v[20:21], off
	global_load_dword v38, v[14:15], off
	v_addc_co_u32_e32 v19, vcc, 0, v3, vcc
	v_add_co_u32_e32 v14, vcc, 0x38000, v2
	s_nop 0
	s_nop 0
	v_addc_co_u32_e32 v15, vcc, 0, v3, vcc
	v_add_co_u32_e32 v20, vcc, 0x3c000, v2
	global_load_dword v40, v[18:19], off
	global_load_dword v42, v[14:15], off
	v_addc_co_u32_e32 v21, vcc, 0, v3, vcc
	v_add_co_u32_e32 v14, vcc, 0x40000, v2
	s_nop 0
	s_nop 0
	v_addc_co_u32_e32 v15, vcc, 0, v3, vcc
	v_add_co_u32_e32 v18, vcc, 0x44000, v2
	global_load_dword v44, v[20:21], off
	global_load_dword v46, v[14:15], off
	v_addc_co_u32_e32 v19, vcc, 0, v3, vcc
	v_add_co_u32_e32 v14, vcc, 0x48000, v2
	global_load_dword v48, v[18:19], off
	s_nop 0
	v_addc_co_u32_e32 v15, vcc, 0, v3, vcc
	v_add_co_u32_e32 v18, vcc, 0x4c000, v2
	s_nop 0
	s_nop 0
	v_addc_co_u32_e32 v19, vcc, 0, v3, vcc
	v_add_co_u32_e32 v20, vcc, 0x50000, v2
	global_load_dword v50, v[14:15], off
	global_load_dword v52, v[18:19], off
	v_addc_co_u32_e32 v21, vcc, 0, v3, vcc
	v_add_co_u32_e32 v14, vcc, 0x54000, v2
	s_nop 0
	s_nop 0
	v_addc_co_u32_e32 v15, vcc, 0, v3, vcc
	v_add_co_u32_e32 v18, vcc, 0x58000, v2
	global_load_dword v54, v[20:21], off
	global_load_dword v56, v[14:15], off
	v_addc_co_u32_e32 v19, vcc, 0, v3, vcc
	v_add_co_u32_e32 v14, vcc, 0x5c000, v2
	s_nop 0
	s_nop 0
	v_addc_co_u32_e32 v15, vcc, 0, v3, vcc
	global_load_dword v57, v[18:19], off
	global_load_dword v58, v[14:15], off
	s_waitcnt vmcnt(12)
	v_and_b32_e32 v37, 0xffff0000, v23
	v_and_b32_e32 v41, 0xffff0000, v25
	v_and_b32_e32 v45, 0xffff0000, v28
	v_and_b32_e32 v49, 0xffff0000, v32
	v_lshlrev_b32_e32 v35, 16, v34
	v_and_b32_e32 v34, 0xffff0000, v34
	v_and_b32_e32 v53, 0xffff0000, v36
	v_and_b32_e32 v20, 0xffff0000, v22
	v_lshlrev_b32_e32 v14, 16, v16
	v_mul_f32_e32 v15, 0x3fb8aa3b, v14
	v_add_f32_e32 v1, v1, v14
	v_exp_f32_e32 v14, v15
	v_lshlrev_b32_e32 v15, 16, v17
	v_and_b32_e32 v18, 0xffff0000, v17
	v_lshlrev_b32_e32 v17, 16, v22
	v_mul_f32_e32 v21, 0x3fb8aa3b, v15
	v_mul_f32_e32 v22, 0x3fb8aa3b, v17
	v_lshlrev_b32_e32 v19, 16, v23
	v_exp_f32_e32 v31, v21
	v_and_b32_e32 v16, 0xffff0000, v16
	v_exp_f32_e32 v22, v22
	v_lshlrev_b32_e32 v21, 16, v24
	v_mul_f32_e32 v23, 0x3fb8aa3b, v19
	v_fmac_f32_e32 v16, v0, v14
	v_mul_f32_e32 v0, 0x3fb8aa3b, v21
	v_exp_f32_e32 v14, v23
	v_lshlrev_b32_e32 v23, 16, v25
	v_exp_f32_e32 v0, v0
	v_lshlrev_b32_e32 v25, 16, v27
	v_mul_f32_e32 v29, 0x3fb8aa3b, v23
	v_mul_f32_e32 v33, 0x3fb8aa3b, v25
	v_exp_f32_e32 v39, v29
	v_lshlrev_b32_e32 v29, 16, v28
	v_fmac_f32_e32 v18, v31, v16
	v_exp_f32_e32 v16, v33
	v_lshlrev_b32_e32 v31, 16, v30
	v_mul_f32_e32 v28, 0x3fb8aa3b, v29
	v_fmac_f32_e32 v20, v22, v18
	v_and_b32_e32 v24, 0xffff0000, v24
	v_mul_f32_e32 v18, 0x3fb8aa3b, v31
	v_exp_f32_e32 v22, v28
	v_lshlrev_b32_e32 v33, 16, v32
	v_fmac_f32_e32 v37, v14, v20
	v_exp_f32_e32 v20, v18
	v_mul_f32_e32 v14, 0x3fb8aa3b, v33
	v_fmac_f32_e32 v24, v0, v37
	v_and_b32_e32 v27, 0xffff0000, v27
	v_mul_f32_e32 v0, 0x3fb8aa3b, v35
	v_exp_f32_e32 v32, v14
	v_lshlrev_b32_e32 v37, 16, v36
	v_fmac_f32_e32 v41, v39, v24
	v_exp_f32_e32 v0, v0
	s_waitcnt vmcnt(11)
	v_lshlrev_b32_e32 v39, 16, v38
	v_mul_f32_e32 v24, 0x3fb8aa3b, v37
	v_fmac_f32_e32 v27, v16, v41
	v_and_b32_e32 v30, 0xffff0000, v30
	v_and_b32_e32 v14, 0xffff0000, v38
	v_mul_f32_e32 v16, 0x3fb8aa3b, v39
	v_exp_f32_e32 v38, v24
	v_fmac_f32_e32 v45, v22, v27
	s_waitcnt vmcnt(10)
	v_lshlrev_b32_e32 v41, 16, v40
	v_exp_f32_e32 v27, v16
	v_fmac_f32_e32 v30, v20, v45
	v_mul_f32_e32 v16, 0x3fb8aa3b, v41
	v_fmac_f32_e32 v49, v32, v30
	v_exp_f32_e32 v16, v16
	s_waitcnt vmcnt(7)
	v_lshlrev_b32_e32 v47, 16, v46
	v_fmac_f32_e32 v34, v0, v49
	v_lshlrev_b32_e32 v43, 16, v42
	v_mul_f32_e32 v0, 0x3fb8aa3b, v47
	v_fmac_f32_e32 v53, v38, v34
	v_mul_f32_e32 v20, 0x3fb8aa3b, v43
	v_exp_f32_e32 v30, v0
	v_mul_f32_e32 v0, v27, v53
	v_exp_f32_e32 v20, v20
	v_pk_add_f32 v[0:1], v[0:1], v[14:15]
	v_lshlrev_b32_e32 v45, 16, v44
	s_waitcnt vmcnt(6)
	v_lshlrev_b32_e32 v49, 16, v48
	v_and_b32_e32 v36, 0xffff0000, v48
	s_waitcnt vmcnt(3)
	v_lshlrev_b32_e32 v53, 16, v54
	v_and_b32_e32 v48, 0xffff0000, v54
	v_pk_mul_f32 v[54:55], v[16:17], v[0:1]
	v_pk_add_f32 v[0:1], v[16:17], v[0:1]
	v_and_b32_e32 v18, 0xffff0000, v40
	v_mul_f32_e32 v24, 0x3fb8aa3b, v45
	v_lshlrev_b32_e32 v15, 16, v52
	v_mov_b32_e32 v55, v1
	v_exp_f32_e32 v24, v24
	v_mul_f32_e32 v0, 0x3fb8aa3b, v15
	v_pk_add_f32 v[18:19], v[54:55], v[18:19]
	v_and_b32_e32 v22, 0xffff0000, v42
	s_waitcnt vmcnt(2)
	v_and_b32_e32 v14, 0xffff0000, v56
	v_exp_f32_e32 v42, v0
	v_lshlrev_b32_e32 v1, 16, v56
	s_waitcnt vmcnt(1)
	v_lshlrev_b32_e32 v17, 16, v57
	v_and_b32_e32 v0, 0xffff0000, v57
	v_pk_mul_f32 v[56:57], v[20:21], v[18:19]
	v_pk_add_f32 v[18:19], v[20:21], v[18:19]
	v_and_b32_e32 v28, 0xffff0000, v44
	v_mov_b32_e32 v57, v19
	v_pk_add_f32 v[18:19], v[56:57], v[22:23]
	v_mul_f32_e32 v34, 0x3fb8aa3b, v49
	v_pk_mul_f32 v[20:21], v[24:25], v[18:19]
	v_pk_add_f32 v[18:19], v[24:25], v[18:19]
	v_exp_f32_e32 v34, v34
	v_mov_b32_e32 v21, v19
	v_pk_add_f32 v[18:19], v[20:21], v[28:29]
	v_lshlrev_b32_e32 v51, 16, v50
	v_pk_mul_f32 v[20:21], v[30:31], v[18:19]
	v_pk_add_f32 v[18:19], v[30:31], v[18:19]
	v_and_b32_e32 v32, 0xffff0000, v46
	v_mul_f32_e32 v27, 0x3fb8aa3b, v51
	v_mov_b32_e32 v21, v19
	v_exp_f32_e32 v38, v27
	v_pk_add_f32 v[18:19], v[20:21], v[32:33]
	v_and_b32_e32 v40, 0xffff0000, v50
	v_pk_mul_f32 v[20:21], v[34:35], v[18:19]
	v_pk_add_f32 v[18:19], v[34:35], v[18:19]
	v_mul_f32_e32 v16, 0x3fb8aa3b, v53
	v_mov_b32_e32 v21, v19
	v_pk_add_f32 v[18:19], v[20:21], v[36:37]
	v_exp_f32_e32 v46, v16
	v_pk_mul_f32 v[20:21], v[38:39], v[18:19]
	v_pk_add_f32 v[18:19], v[38:39], v[18:19]
	v_and_b32_e32 v44, 0xffff0000, v52
	v_mov_b32_e32 v21, v19
	v_pk_add_f32 v[18:19], v[20:21], v[40:41]
	v_mul_f32_e32 v16, 0x3fb8aa3b, v1
	v_pk_mul_f32 v[20:21], v[42:43], v[18:19]
	v_pk_add_f32 v[18:19], v[42:43], v[18:19]
	v_exp_f32_e32 v50, v16
	v_mov_b32_e32 v21, v19
	v_pk_add_f32 v[18:19], v[20:21], v[44:45]
	v_mul_f32_e32 v27, 0x3fb8aa3b, v17
	v_pk_mul_f32 v[20:21], v[46:47], v[18:19]
	v_pk_add_f32 v[18:19], v[46:47], v[18:19]
	v_exp_f32_e32 v52, v27
	v_mov_b32_e32 v21, v19
	v_pk_add_f32 v[18:19], v[20:21], v[48:49]
	s_waitcnt vmcnt(0)
	v_lshlrev_b32_e32 v55, 16, v58
	v_pk_mul_f32 v[20:21], v[50:51], v[18:19]
	v_pk_add_f32 v[18:19], v[50:51], v[18:19]
	v_mul_f32_e32 v16, 0x3fb8aa3b, v55
	v_mov_b32_e32 v21, v19
	v_exp_f32_e32 v16, v16
	v_pk_add_f32 v[14:15], v[20:21], v[14:15]
	v_and_b32_e32 v54, 0xffff0000, v58
	v_pk_mul_f32 v[18:19], v[52:53], v[14:15]
	v_pk_add_f32 v[14:15], v[52:53], v[14:15]
	v_lshl_add_u64 v[2:3], v[2:3], 0, s[26:27]
	v_mov_b32_e32 v19, v15
	v_pk_add_f32 v[0:1], v[18:19], v[0:1]
	s_nop 0
	v_pk_mul_f32 v[14:15], v[16:17], v[0:1]
	v_pk_add_f32 v[0:1], v[16:17], v[0:1]
	s_nop 0
	v_mov_b32_e32 v15, v1
	v_pk_add_f32 v[0:1], v[14:15], v[54:55]
	s_cbranch_scc0 .LBB0_1042
	s_lshl_b32 s20, s50, 6
	v_readlane_b32 s23, v254, 16
	s_and_b32 s20, s20, 0xfc0
	s_mul_i32 s21, s24, 0x810
	s_mul_i32 s22, s23, 0x102
	v_add_u32_e32 v14, s20, v4
	s_mul_hi_i32 s20, s24, 0x810
	s_add_u32 s26, s21, s22
	s_mul_hi_u32 s21, s23, 0x102
	s_addc_u32 s27, s20, s21
	s_lshl_b64 s[20:21], s[26:27], 14
	v_readlane_b32 s52, v254, 33
	s_add_u32 s20, s52, s20
	s_addc_u32 s21, s77, s21
	v_ashrrev_i32_e32 v15, 31, v14
	v_lshl_add_u64 v[18:19], v[14:15], 2, s[20:21]
	s_mov_b32 s20, 0x3c0000
	v_add_co_u32_e32 v2, vcc, s20, v18
	s_mov_b32 s20, 0x3c4000
	s_nop 0
	v_addc_co_u32_e32 v3, vcc, 0, v19, vcc
	global_load_dword v16, v[2:3], off
	v_add_co_u32_e32 v2, vcc, s20, v18
	s_mov_b32 s20, 0x3c8000
	s_nop 0
	v_addc_co_u32_e32 v3, vcc, 0, v19, vcc
	global_load_dword v17, v[2:3], off
	v_add_co_u32_e32 v2, vcc, s20, v18
	s_mov_b32 s20, 0x3cc000
	s_nop 0
	v_addc_co_u32_e32 v3, vcc, 0, v19, vcc
	global_load_dword v20, v[2:3], off
	v_add_co_u32_e32 v2, vcc, s20, v18
	s_mov_b32 s20, 0x3d0000
	s_nop 0
	v_addc_co_u32_e32 v3, vcc, 0, v19, vcc
	global_load_dword v21, v[2:3], off
	v_add_co_u32_e32 v2, vcc, s20, v18
	s_mov_b32 s20, 0x3d4000
	s_nop 0
	v_addc_co_u32_e32 v3, vcc, 0, v19, vcc
	global_load_dword v22, v[2:3], off
	v_add_co_u32_e32 v2, vcc, s20, v18
	s_mov_b32 s20, 0x3d8000
	s_nop 0
	v_addc_co_u32_e32 v3, vcc, 0, v19, vcc
	global_load_dword v23, v[2:3], off
	v_add_co_u32_e32 v2, vcc, s20, v18
	s_mov_b32 s20, 0x3dc000
	s_nop 0
	v_addc_co_u32_e32 v3, vcc, 0, v19, vcc
	global_load_dword v24, v[2:3], off
	v_add_co_u32_e32 v2, vcc, s20, v18
	s_mov_b32 s20, 0x3e0000
	s_nop 0
	v_addc_co_u32_e32 v3, vcc, 0, v19, vcc
	global_load_dword v25, v[2:3], off
	v_add_co_u32_e32 v2, vcc, s20, v18
	s_mov_b32 s20, 0x3e4000
	s_nop 0
	v_addc_co_u32_e32 v3, vcc, 0, v19, vcc
	global_load_dword v27, v[2:3], off
	v_add_co_u32_e32 v2, vcc, s20, v18
	s_mov_b32 s20, 0x3e8000
	s_nop 0
	v_addc_co_u32_e32 v3, vcc, 0, v19, vcc
	global_load_dword v28, v[2:3], off
	v_add_co_u32_e32 v2, vcc, s20, v18
	s_mov_b32 s20, 0x3ec000
	s_nop 0
	v_addc_co_u32_e32 v3, vcc, 0, v19, vcc
	global_load_dword v29, v[2:3], off
	v_add_co_u32_e32 v2, vcc, s20, v18
	s_mov_b32 s20, 0x3f0000
	s_nop 0
	v_addc_co_u32_e32 v3, vcc, 0, v19, vcc
	global_load_dword v30, v[2:3], off
	v_add_co_u32_e32 v2, vcc, s20, v18
	s_mov_b32 s20, 0x3f4000
	s_nop 0
	v_addc_co_u32_e32 v3, vcc, 0, v19, vcc
	global_load_dword v31, v[2:3], off
	v_add_co_u32_e32 v2, vcc, s20, v18
	s_mov_b32 s20, 0x3f8000
	s_nop 0
	v_addc_co_u32_e32 v3, vcc, 0, v19, vcc
	global_load_dword v32, v[2:3], off
	v_add_co_u32_e32 v2, vcc, s20, v18
	s_mov_b32 s20, 0x3fc000
	s_nop 0
	v_addc_co_u32_e32 v3, vcc, 0, v19, vcc
	global_load_dword v33, v[2:3], off
	v_add_co_u32_e32 v2, vcc, s20, v18
	s_mov_b32 s20, 0x400000
	s_nop 0
	v_addc_co_u32_e32 v3, vcc, 0, v19, vcc
	global_load_dword v34, v[2:3], off
	v_add_co_u32_e32 v2, vcc, s20, v18
	s_mov_b32 s20, 0x404000
	s_nop 0
	v_addc_co_u32_e32 v3, vcc, 0, v19, vcc
	global_load_dword v35, v[2:3], off
	v_add_co_u32_e32 v2, vcc, s20, v18
	v_readlane_b32 s20, v255, 3
	s_nop 0
	v_addc_co_u32_e32 v3, vcc, 0, v19, vcc
	global_load_dword v2, v[2:3], off
	s_waitcnt vmcnt(17)
	v_lshlrev_b32_e32 v3, 16, v16
	v_mul_f32_e32 v36, 0x3fb8aa3b, v3
	v_exp_f32_e32 v36, v36
	v_and_b32_e32 v16, 0xffff0000, v16
	v_readlane_b32 s21, v255, 4
	s_andn2_b64 vcc, exec, s[20:21]
	v_fmac_f32_e32 v16, v0, v36
	v_add_f32_e32 v0, v1, v3
	s_waitcnt vmcnt(16)
	v_lshlrev_b32_e32 v1, 16, v17
	v_mul_f32_e32 v3, 0x3fb8aa3b, v1
	v_exp_f32_e32 v3, v3
	v_and_b32_e32 v17, 0xffff0000, v17
	v_add_f32_e32 v0, v0, v1
	s_waitcnt vmcnt(15)
	v_lshlrev_b32_e32 v1, 16, v20
	v_fmac_f32_e32 v17, v3, v16
	v_mul_f32_e32 v3, 0x3fb8aa3b, v1
	v_exp_f32_e32 v3, v3
	v_and_b32_e32 v16, 0xffff0000, v20
	v_add_f32_e32 v0, v0, v1
	s_waitcnt vmcnt(14)
	v_lshlrev_b32_e32 v1, 16, v21
	v_fmac_f32_e32 v16, v3, v17
	v_mul_f32_e32 v3, 0x3fb8aa3b, v1
	v_exp_f32_e32 v3, v3
	v_and_b32_e32 v17, 0xffff0000, v21
	v_add_f32_e32 v0, v0, v1
	s_waitcnt vmcnt(13)
	v_lshlrev_b32_e32 v1, 16, v22
	v_fmac_f32_e32 v17, v3, v16
	v_mul_f32_e32 v3, 0x3fb8aa3b, v1
	v_exp_f32_e32 v3, v3
	v_and_b32_e32 v16, 0xffff0000, v22
	v_add_f32_e32 v0, v0, v1
	s_waitcnt vmcnt(12)
	v_lshlrev_b32_e32 v1, 16, v23
	v_fmac_f32_e32 v16, v3, v17
	v_mul_f32_e32 v3, 0x3fb8aa3b, v1
	v_exp_f32_e32 v3, v3
	v_and_b32_e32 v17, 0xffff0000, v23
	v_add_f32_e32 v0, v0, v1
	s_waitcnt vmcnt(11)
	v_lshlrev_b32_e32 v1, 16, v24
	v_fmac_f32_e32 v17, v3, v16
	v_mul_f32_e32 v3, 0x3fb8aa3b, v1
	v_exp_f32_e32 v3, v3
	v_and_b32_e32 v16, 0xffff0000, v24
	v_add_f32_e32 v0, v0, v1
	s_waitcnt vmcnt(10)
	v_lshlrev_b32_e32 v1, 16, v25
	v_fmac_f32_e32 v16, v3, v17
	v_mul_f32_e32 v3, 0x3fb8aa3b, v1
	v_exp_f32_e32 v3, v3
	v_and_b32_e32 v17, 0xffff0000, v25
	v_add_f32_e32 v0, v0, v1
	s_waitcnt vmcnt(9)
	v_lshlrev_b32_e32 v1, 16, v27
	v_fmac_f32_e32 v17, v3, v16
	v_mul_f32_e32 v3, 0x3fb8aa3b, v1
	v_exp_f32_e32 v3, v3
	v_and_b32_e32 v16, 0xffff0000, v27
	v_add_f32_e32 v0, v0, v1
	s_waitcnt vmcnt(8)
	v_lshlrev_b32_e32 v1, 16, v28
	v_fmac_f32_e32 v16, v3, v17
	v_mul_f32_e32 v3, 0x3fb8aa3b, v1
	v_exp_f32_e32 v3, v3
	v_and_b32_e32 v17, 0xffff0000, v28
	v_add_f32_e32 v0, v0, v1
	s_waitcnt vmcnt(7)
	v_lshlrev_b32_e32 v1, 16, v29
	v_fmac_f32_e32 v17, v3, v16
	v_mul_f32_e32 v3, 0x3fb8aa3b, v1
	v_exp_f32_e32 v3, v3
	v_and_b32_e32 v16, 0xffff0000, v29
	v_add_f32_e32 v0, v0, v1
	s_waitcnt vmcnt(6)
	v_lshlrev_b32_e32 v1, 16, v30
	v_fmac_f32_e32 v16, v3, v17
	v_mul_f32_e32 v3, 0x3fb8aa3b, v1
	v_exp_f32_e32 v3, v3
	v_and_b32_e32 v17, 0xffff0000, v30
	v_add_f32_e32 v0, v0, v1
	s_waitcnt vmcnt(5)
	v_lshlrev_b32_e32 v1, 16, v31
	v_fmac_f32_e32 v17, v3, v16
	v_mul_f32_e32 v3, 0x3fb8aa3b, v1
	v_exp_f32_e32 v3, v3
	v_and_b32_e32 v16, 0xffff0000, v31
	v_add_f32_e32 v0, v0, v1
	s_waitcnt vmcnt(4)
	v_lshlrev_b32_e32 v1, 16, v32
	v_fmac_f32_e32 v16, v3, v17
	v_mul_f32_e32 v3, 0x3fb8aa3b, v1
	v_exp_f32_e32 v3, v3
	v_and_b32_e32 v17, 0xffff0000, v32
	v_add_f32_e32 v0, v0, v1
	s_waitcnt vmcnt(3)
	v_lshlrev_b32_e32 v1, 16, v33
	v_fmac_f32_e32 v17, v3, v16
	v_mul_f32_e32 v3, 0x3fb8aa3b, v1
	v_exp_f32_e32 v3, v3
	v_and_b32_e32 v16, 0xffff0000, v33
	v_add_f32_e32 v0, v0, v1
	s_waitcnt vmcnt(2)
	v_lshlrev_b32_e32 v1, 16, v34
	v_fmac_f32_e32 v16, v3, v17
	v_mul_f32_e32 v3, 0x3fb8aa3b, v1
	v_exp_f32_e32 v3, v3
	v_and_b32_e32 v17, 0xffff0000, v34
	v_add_f32_e32 v0, v0, v1
	s_waitcnt vmcnt(1)
	v_lshlrev_b32_e32 v1, 16, v35
	v_fmac_f32_e32 v17, v3, v16
	v_mul_f32_e32 v3, 0x3fb8aa3b, v1
	v_exp_f32_e32 v3, v3
	v_and_b32_e32 v16, 0xffff0000, v35
	v_add_f32_e32 v0, v0, v1
	v_readlane_b32 s53, v254, 34
	v_fmac_f32_e32 v16, v3, v17
	s_waitcnt vmcnt(0)
	v_lshlrev_b32_e32 v3, 16, v2
	v_mul_f32_e32 v1, 0x3fb8aa3b, v3
	v_add_f32_e32 v0, v0, v3
	v_exp_f32_e32 v17, v1
	v_mul_f32_e32 v0, 0x3fb8aa3b, v0
	v_exp_f32_e32 v0, v0
	v_and_b32_e32 v1, 0xffff0000, v2
	v_fmac_f32_e32 v1, v17, v16
	v_mov_b32_e32 v3, 0
	v_readlane_b32 s54, v254, 35
	v_readlane_b32 s55, v254, 36
	ds_write_b64 v5, v[0:1]
	s_waitcnt lgkmcnt(0)
	s_barrier
	s_cbranch_vccnz .LBB0_1051
	s_andn2_b64 vcc, exec, s[6:7]
	s_cbranch_vccnz .LBB0_1048
	s_mov_b32 s20, 0
	v_mov_b32_e32 v3, 0
	v_mov_b32_e32 v16, v26
